# second/third down GEMM (dnL0b, dnL1a) in-place residual epilogues rewritten: loads in flight, 32-bit offsets via SGPR base, accumulator map parsed by dataflow
# speedup vs baseline: 1.0148x; 1.0089x over previous
; __device__ __forceinline__ unsigned cvt_pk_bf16(float lo, float hi) { unsigned r; asm("v_cvt_pk_bf16_f32 %0, %1, %2" : "=v"(r) : "v"(lo), "v"(hi)); return r; }
;     __device__ __forceinline__ void operator()(const Acc& acc, const Unit& u, int wr, int wc, int fr, int fq) const {
;         const bool isx = u.pm < 128; const int mb = isx ? (u.pm >> 4) : 8;
;         const size_t tile0 = (size_t)(isx ? u.pm : u.pm - 128) * 256 * D;
;         const float* sp32 = (const float*)(isx ? srcx : srcc) + tile0; const bf16_t* sp16 = (const bf16_t*)(isx ? srcx : srcc) + tile0;
;         float* dp32 = (float*)(isx ? dstx : dstc) + tile0; bf16_t* dp16 = (bf16_t*)(isx ? dstx : dstc) + tile0;
;         const int r0 = wr * 64 + fr, col0 = u.pn * 256 + wc * 32 + 8 * fq; const float* gp = gate + (size_t)mb * 9216 + col0;
;         f32x4 gv[2][2];
; #pragma unroll
;         for (int bj = 0; bj < 2; ++bj)
; #pragma unroll
;             for (int n = 0; n < 2; ++n) gv[bj][n] = *(const f32x4*)(gp + bj * 128 + n * 4) * f;
; #pragma unroll
;         for (int ai = 0; ai < 2; ++ai)
; #pragma unroll
;             for (int m = 0; m < 4; ++m) { const size_t off = (size_t)(r0 + ai * 128 + m * 16) * D + col0;
; #pragma unroll
;                 for (int bj = 0; bj < 2; ++bj) { const size_t o2 = off + bj * 128; f32x4 s0, s1;
;                     if (SRC32) { s0 = *(const f32x4*)(sp32 + o2); s1 = *(const f32x4*)(sp32 + o2 + 4); }
;                     else { const u32x4 q = *(const u32x4*)(sp16 + o2); s0 = (f32x4){bf2f(q.x & 0xffffu), bf2f(q.x >> 16), bf2f(q.y & 0xffffu), bf2f(q.y >> 16)}; s1 = (f32x4){bf2f(q.z & 0xffffu), bf2f(q.z >> 16), bf2f(q.w & 0xffffu), bf2f(q.w >> 16)}; }
;                     const f32x4 v0 = s0 + gv[bj][0] * acc[ai][bj][m][0], v1 = s1 + gv[bj][1] * acc[ai][bj][m][1];
;                     if (DST32) { *(f32x4*)(dp32 + o2) = v0; *(f32x4*)(dp32 + o2 + 4) = v1; }
;                     else { u32x4 w; w.x = cvt_pk_bf16(v0.x, v0.y); w.y = cvt_pk_bf16(v0.z, v0.w); w.z = cvt_pk_bf16(v1.x, v1.y); w.w = cvt_pk_bf16(v1.z, v1.w); *(u32x4*)(dp16 + o2) = w; } } }
.LBB0_1126:
	s_add_i32 s38, s56, 0xffffff80
	s_and_b64 s[36:37], s[36:37], exec
	s_cselect_b32 s36, s56, s38
	s_ashr_i32 s37, s36, 31
	s_lshl_b64 s[34:35], s[34:35], 2
	v_lshl_or_b32 v238, s57, 8, v209
	s_add_u32 s34, s46, s34
	s_addc_u32 s35, s47, s35
	v_lshlrev_b32_e32 v234, 2, v238
	global_load_dwordx4 v[128:131], v234, s[34:35]
	global_load_dwordx4 v[132:135], v234, s[34:35] offset:16
	global_load_dwordx4 v[136:139], v234, s[34:35] offset:512
	global_load_dwordx4 v[140:143], v234, s[34:35] offset:528
	s_lshl_b64 s[34:35], s[36:37], 19
	s_add_u32 s34, s86, s34
	s_addc_u32 s35, s87, s35
	v_lshl_add_u32 v235, v238, 1, v164
	global_load_dwordx4 v[144:147], v235, s[34:35]
	global_load_dwordx4 v[148:151], v235, s[34:35] offset:256
	v_lshl_add_u32 v234, v238, 1, v174
	global_load_dwordx4 v[152:155], v234, s[34:35]
	global_load_dwordx4 v[156:159], v234, s[34:35] offset:256
	v_lshl_add_u32 v235, v238, 1, v176
	global_load_dwordx4 v[188:191], v235, s[34:35]
	global_load_dwordx4 v[192:195], v235, s[34:35] offset:256
	v_lshl_add_u32 v234, v238, 1, v178
	global_load_dwordx4 v[196:199], v234, s[34:35]
	global_load_dwordx4 v[200:203], v234, s[34:35] offset:256
	v_lshl_add_u32 v235, v238, 1, v166
	global_load_dwordx4 v[214:217], v235, s[34:35]
	global_load_dwordx4 v[218:221], v235, s[34:35] offset:256
	v_lshl_add_u32 v234, v238, 1, v168
	global_load_dwordx4 v[222:225], v234, s[34:35]
	global_load_dwordx4 v[226:229], v234, s[34:35] offset:256
	s_waitcnt vmcnt(11)
	v_pk_mul_f32 v[128:129], v[128:129], 0.5 op_sel_hi:[1,0]
	v_pk_mul_f32 v[130:131], v[130:131], 0.5 op_sel_hi:[1,0]
	v_pk_mul_f32 v[132:133], v[132:133], 0.5 op_sel_hi:[1,0]
	v_pk_mul_f32 v[134:135], v[134:135], 0.5 op_sel_hi:[1,0]
	v_pk_mul_f32 v[136:137], v[136:137], 0.5 op_sel_hi:[1,0]
	v_pk_mul_f32 v[138:139], v[138:139], 0.5 op_sel_hi:[1,0]
	v_pk_mul_f32 v[140:141], v[140:141], 0.5 op_sel_hi:[1,0]
	v_pk_mul_f32 v[142:143], v[142:143], 0.5 op_sel_hi:[1,0]
	v_lshlrev_b32_e32 v230, 16, v144
	v_and_b32_e32 v231, 0xffff0000, v144
	v_lshlrev_b32_e32 v232, 16, v145
	v_and_b32_e32 v233, 0xffff0000, v145
	v_lshlrev_b32_e32 v144, 16, v146
	v_and_b32_e32 v145, 0xffff0000, v146
	v_lshlrev_b32_e32 v146, 16, v147
	v_and_b32_e32 v147, 0xffff0000, v147
	v_pk_fma_f32 v[124:125], v[124:125], v[128:129], v[230:231]
	v_pk_fma_f32 v[126:127], v[126:127], v[130:131], v[232:233]
	v_pk_fma_f32 v[120:121], v[120:121], v[132:133], v[144:145]
	v_pk_fma_f32 v[122:123], v[122:123], v[134:135], v[146:147]
	v_cvt_pk_bf16_f32 v124, v124, v125
	v_cvt_pk_bf16_f32 v125, v126, v127
	v_cvt_pk_bf16_f32 v126, v120, v121
	v_cvt_pk_bf16_f32 v127, v122, v123
	s_waitcnt vmcnt(10)
	v_lshlrev_b32_e32 v230, 16, v148
	v_and_b32_e32 v231, 0xffff0000, v148
	v_lshlrev_b32_e32 v232, 16, v149
	v_and_b32_e32 v233, 0xffff0000, v149
	v_lshlrev_b32_e32 v148, 16, v150
	v_and_b32_e32 v149, 0xffff0000, v150
	v_lshlrev_b32_e32 v150, 16, v151
	v_and_b32_e32 v151, 0xffff0000, v151
	v_pk_fma_f32 v[108:109], v[108:109], v[136:137], v[230:231]
	v_pk_fma_f32 v[110:111], v[110:111], v[138:139], v[232:233]
	v_pk_fma_f32 v[104:105], v[104:105], v[140:141], v[148:149]
	v_pk_fma_f32 v[106:107], v[106:107], v[142:143], v[150:151]
	v_cvt_pk_bf16_f32 v108, v108, v109
	v_cvt_pk_bf16_f32 v109, v110, v111
	v_cvt_pk_bf16_f32 v110, v104, v105
	v_cvt_pk_bf16_f32 v111, v106, v107
	s_waitcnt vmcnt(9)
	v_lshlrev_b32_e32 v230, 16, v152
	v_and_b32_e32 v231, 0xffff0000, v152
	v_lshlrev_b32_e32 v232, 16, v153
	v_and_b32_e32 v233, 0xffff0000, v153
	v_lshlrev_b32_e32 v152, 16, v154
	v_and_b32_e32 v153, 0xffff0000, v154
	v_lshlrev_b32_e32 v154, 16, v155
	v_and_b32_e32 v155, 0xffff0000, v155
	v_pk_fma_f32 v[116:117], v[116:117], v[128:129], v[230:231]
	v_pk_fma_f32 v[118:119], v[118:119], v[130:131], v[232:233]
	v_pk_fma_f32 v[112:113], v[112:113], v[132:133], v[152:153]
	v_pk_fma_f32 v[114:115], v[114:115], v[134:135], v[154:155]
	v_cvt_pk_bf16_f32 v116, v116, v117
	v_cvt_pk_bf16_f32 v117, v118, v119
	v_cvt_pk_bf16_f32 v118, v112, v113
	v_cvt_pk_bf16_f32 v119, v114, v115
	s_waitcnt vmcnt(8)
	v_lshlrev_b32_e32 v230, 16, v156
	v_and_b32_e32 v231, 0xffff0000, v156
	v_lshlrev_b32_e32 v232, 16, v157
	v_and_b32_e32 v233, 0xffff0000, v157
	v_lshlrev_b32_e32 v156, 16, v158
	v_and_b32_e32 v157, 0xffff0000, v158
	v_lshlrev_b32_e32 v158, 16, v159
	v_and_b32_e32 v159, 0xffff0000, v159
	v_pk_fma_f32 v[100:101], v[100:101], v[136:137], v[230:231]
	v_pk_fma_f32 v[102:103], v[102:103], v[138:139], v[232:233]
	v_pk_fma_f32 v[96:97], v[96:97], v[140:141], v[156:157]
	v_pk_fma_f32 v[98:99], v[98:99], v[142:143], v[158:159]
	v_cvt_pk_bf16_f32 v100, v100, v101
	v_cvt_pk_bf16_f32 v101, v102, v103
	v_cvt_pk_bf16_f32 v102, v96, v97
	v_cvt_pk_bf16_f32 v103, v98, v99
	v_lshl_add_u32 v235, v238, 1, v170
	global_load_dwordx4 v[144:147], v235, s[34:35]
	global_load_dwordx4 v[148:151], v235, s[34:35] offset:256
	v_lshl_add_u32 v234, v238, 1, v172
	global_load_dwordx4 v[152:155], v234, s[34:35]
	global_load_dwordx4 v[156:159], v234, s[34:35] offset:256
	s_waitcnt vmcnt(11)
	v_lshlrev_b32_e32 v230, 16, v188
	v_and_b32_e32 v231, 0xffff0000, v188
	v_lshlrev_b32_e32 v232, 16, v189
	v_and_b32_e32 v233, 0xffff0000, v189
	v_lshlrev_b32_e32 v188, 16, v190
	v_and_b32_e32 v189, 0xffff0000, v190
	v_lshlrev_b32_e32 v190, 16, v191
	v_and_b32_e32 v191, 0xffff0000, v191
	v_pk_fma_f32 v[92:93], v[92:93], v[128:129], v[230:231]
	v_pk_fma_f32 v[94:95], v[94:95], v[130:131], v[232:233]
	v_pk_fma_f32 v[88:89], v[88:89], v[132:133], v[188:189]
	v_pk_fma_f32 v[90:91], v[90:91], v[134:135], v[190:191]
	v_cvt_pk_bf16_f32 v92, v92, v93
	v_cvt_pk_bf16_f32 v93, v94, v95
	v_cvt_pk_bf16_f32 v94, v88, v89
	v_cvt_pk_bf16_f32 v95, v90, v91
	s_waitcnt vmcnt(10)
; __device__ __forceinline__ unsigned cvt_pk_bf16(float lo, float hi) { unsigned r; asm("v_cvt_pk_bf16_f32 %0, %1, %2" : "=v"(r) : "v"(lo), "v"(hi)); return r; }
;     __device__ __forceinline__ void operator()(const Acc& acc, const Unit& u, int wr, int wc, int fr, int fq) const {
;     ...
;             for (int m = 0; m < 4; ++m) { const size_t off = (size_t)(r0 + ai * 128 + m * 16) * D + col0;
; #pragma unroll
;                 for (int bj = 0; bj < 2; ++bj) { const size_t o2 = off + bj * 128; f32x4 s0, s1;
;                     if (SRC32) { s0 = *(const f32x4*)(sp32 + o2); s1 = *(const f32x4*)(sp32 + o2 + 4); }
;                     else { const u32x4 q = *(const u32x4*)(sp16 + o2); s0 = (f32x4){bf2f(q.x & 0xffffu), bf2f(q.x >> 16), bf2f(q.y & 0xffffu), bf2f(q.y >> 16)}; s1 = (f32x4){bf2f(q.z & 0xffffu), bf2f(q.z >> 16), bf2f(q.w & 0xffffu), bf2f(q.w >> 16)}; }
;                     const f32x4 v0 = s0 + gv[bj][0] * acc[ai][bj][m][0], v1 = s1 + gv[bj][1] * acc[ai][bj][m][1];
;                     if (DST32) { *(f32x4*)(dp32 + o2) = v0; *(f32x4*)(dp32 + o2 + 4) = v1; }
;                     else { u32x4 w; w.x = cvt_pk_bf16(v0.x, v0.y); w.y = cvt_pk_bf16(v0.z, v0.w); w.z = cvt_pk_bf16(v1.x, v1.y); w.w = cvt_pk_bf16(v1.z, v1.w); *(u32x4*)(dp16 + o2) = w; } } }
	v_lshlrev_b32_e32 v230, 16, v192
	v_and_b32_e32 v231, 0xffff0000, v192
	v_lshlrev_b32_e32 v232, 16, v193
	v_and_b32_e32 v233, 0xffff0000, v193
	v_lshlrev_b32_e32 v192, 16, v194
	v_and_b32_e32 v193, 0xffff0000, v194
	v_lshlrev_b32_e32 v194, 16, v195
	v_and_b32_e32 v195, 0xffff0000, v195
	v_pk_fma_f32 v[84:85], v[84:85], v[136:137], v[230:231]
	v_pk_fma_f32 v[86:87], v[86:87], v[138:139], v[232:233]
	v_pk_fma_f32 v[80:81], v[80:81], v[140:141], v[192:193]
	v_pk_fma_f32 v[82:83], v[82:83], v[142:143], v[194:195]
	v_cvt_pk_bf16_f32 v84, v84, v85
	v_cvt_pk_bf16_f32 v85, v86, v87
	v_cvt_pk_bf16_f32 v86, v80, v81
	v_cvt_pk_bf16_f32 v87, v82, v83
	s_waitcnt vmcnt(9)
	v_lshlrev_b32_e32 v230, 16, v196
	v_and_b32_e32 v231, 0xffff0000, v196
	v_lshlrev_b32_e32 v232, 16, v197
	v_and_b32_e32 v233, 0xffff0000, v197
	v_lshlrev_b32_e32 v196, 16, v198
	v_and_b32_e32 v197, 0xffff0000, v198
	v_lshlrev_b32_e32 v198, 16, v199
	v_and_b32_e32 v199, 0xffff0000, v199
	v_pk_fma_f32 v[76:77], v[76:77], v[128:129], v[230:231]
	v_pk_fma_f32 v[78:79], v[78:79], v[130:131], v[232:233]
	v_pk_fma_f32 v[72:73], v[72:73], v[132:133], v[196:197]
	v_pk_fma_f32 v[74:75], v[74:75], v[134:135], v[198:199]
	v_cvt_pk_bf16_f32 v76, v76, v77
	v_cvt_pk_bf16_f32 v77, v78, v79
	v_cvt_pk_bf16_f32 v78, v72, v73
	v_cvt_pk_bf16_f32 v79, v74, v75
	s_waitcnt vmcnt(8)
	v_lshlrev_b32_e32 v230, 16, v200
	v_and_b32_e32 v231, 0xffff0000, v200
	v_lshlrev_b32_e32 v232, 16, v201
	v_and_b32_e32 v233, 0xffff0000, v201
	v_lshlrev_b32_e32 v200, 16, v202
	v_and_b32_e32 v201, 0xffff0000, v202
	v_lshlrev_b32_e32 v202, 16, v203
	v_and_b32_e32 v203, 0xffff0000, v203
	v_pk_fma_f32 v[68:69], v[68:69], v[136:137], v[230:231]
	v_pk_fma_f32 v[70:71], v[70:71], v[138:139], v[232:233]
	v_pk_fma_f32 v[64:65], v[64:65], v[140:141], v[200:201]
	v_pk_fma_f32 v[66:67], v[66:67], v[142:143], v[202:203]
	v_cvt_pk_bf16_f32 v68, v68, v69
	v_cvt_pk_bf16_f32 v69, v70, v71
	v_cvt_pk_bf16_f32 v70, v64, v65
	v_cvt_pk_bf16_f32 v71, v66, v67
	s_waitcnt vmcnt(7)
	v_lshlrev_b32_e32 v230, 16, v214
	v_and_b32_e32 v231, 0xffff0000, v214
	v_lshlrev_b32_e32 v232, 16, v215
	v_and_b32_e32 v233, 0xffff0000, v215
	v_lshlrev_b32_e32 v214, 16, v216
	v_and_b32_e32 v215, 0xffff0000, v216
	v_lshlrev_b32_e32 v216, 16, v217
	v_and_b32_e32 v217, 0xffff0000, v217
	v_pk_fma_f32 v[60:61], v[60:61], v[128:129], v[230:231]
	v_pk_fma_f32 v[62:63], v[62:63], v[130:131], v[232:233]
	v_pk_fma_f32 v[56:57], v[56:57], v[132:133], v[214:215]
	v_pk_fma_f32 v[58:59], v[58:59], v[134:135], v[216:217]
	v_cvt_pk_bf16_f32 v60, v60, v61
	v_cvt_pk_bf16_f32 v61, v62, v63
	v_cvt_pk_bf16_f32 v62, v56, v57
	v_cvt_pk_bf16_f32 v63, v58, v59
	s_waitcnt vmcnt(6)
	v_lshlrev_b32_e32 v230, 16, v218
	v_and_b32_e32 v231, 0xffff0000, v218
	v_lshlrev_b32_e32 v232, 16, v219
	v_and_b32_e32 v233, 0xffff0000, v219
	v_lshlrev_b32_e32 v218, 16, v220
	v_and_b32_e32 v219, 0xffff0000, v220
	v_lshlrev_b32_e32 v220, 16, v221
	v_and_b32_e32 v221, 0xffff0000, v221
	v_pk_fma_f32 v[52:53], v[52:53], v[136:137], v[230:231]
	v_pk_fma_f32 v[54:55], v[54:55], v[138:139], v[232:233]
	v_pk_fma_f32 v[48:49], v[48:49], v[140:141], v[218:219]
	v_pk_fma_f32 v[50:51], v[50:51], v[142:143], v[220:221]
	v_cvt_pk_bf16_f32 v52, v52, v53
	v_cvt_pk_bf16_f32 v53, v54, v55
	v_cvt_pk_bf16_f32 v54, v48, v49
	v_cvt_pk_bf16_f32 v55, v50, v51
	s_waitcnt vmcnt(5)
	v_lshlrev_b32_e32 v230, 16, v222
	v_and_b32_e32 v231, 0xffff0000, v222
	v_lshlrev_b32_e32 v232, 16, v223
	v_and_b32_e32 v233, 0xffff0000, v223
	v_lshlrev_b32_e32 v222, 16, v224
	v_and_b32_e32 v223, 0xffff0000, v224
	v_lshlrev_b32_e32 v224, 16, v225
	v_and_b32_e32 v225, 0xffff0000, v225
	v_pk_fma_f32 v[44:45], v[44:45], v[128:129], v[230:231]
	v_pk_fma_f32 v[46:47], v[46:47], v[130:131], v[232:233]
	v_pk_fma_f32 v[40:41], v[40:41], v[132:133], v[222:223]
	v_pk_fma_f32 v[42:43], v[42:43], v[134:135], v[224:225]
	v_cvt_pk_bf16_f32 v44, v44, v45
	v_cvt_pk_bf16_f32 v45, v46, v47
	v_cvt_pk_bf16_f32 v46, v40, v41
	v_cvt_pk_bf16_f32 v47, v42, v43
	s_waitcnt vmcnt(4)
; __device__ __forceinline__ unsigned cvt_pk_bf16(float lo, float hi) { unsigned r; asm("v_cvt_pk_bf16_f32 %0, %1, %2" : "=v"(r) : "v"(lo), "v"(hi)); return r; }
; #define PG8_BAR __builtin_amdgcn_s_barrier()
; template <class Epi, class Sched, bool SWAPD = false>
; __device__ __forceinline__ void gemm_phase(LAS unsigned char* lds, const Gemm g, const Sched& S, const Epi& E) {
;     ...
;         cur = nxt; cA = nA; cB = nB; ++ui;
;         if (wr == 1) PG8_BAR;
;     __device__ __forceinline__ void operator()(const Acc& acc, const Unit& u, int wr, int wc, int fr, int fq) const {
;     ...
;             for (int m = 0; m < 4; ++m) { const size_t off = (size_t)(r0 + ai * 128 + m * 16) * D + col0;
; #pragma unroll
;                 for (int bj = 0; bj < 2; ++bj) { const size_t o2 = off + bj * 128; f32x4 s0, s1;
;                     if (SRC32) { s0 = *(const f32x4*)(sp32 + o2); s1 = *(const f32x4*)(sp32 + o2 + 4); }
;                     else { const u32x4 q = *(const u32x4*)(sp16 + o2); s0 = (f32x4){bf2f(q.x & 0xffffu), bf2f(q.x >> 16), bf2f(q.y & 0xffffu), bf2f(q.y >> 16)}; s1 = (f32x4){bf2f(q.z & 0xffffu), bf2f(q.z >> 16), bf2f(q.w & 0xffffu), bf2f(q.w >> 16)}; }
;                     const f32x4 v0 = s0 + gv[bj][0] * acc[ai][bj][m][0], v1 = s1 + gv[bj][1] * acc[ai][bj][m][1];
;                     if (DST32) { *(f32x4*)(dp32 + o2) = v0; *(f32x4*)(dp32 + o2 + 4) = v1; }
;                     else { u32x4 w; w.x = cvt_pk_bf16(v0.x, v0.y); w.y = cvt_pk_bf16(v0.z, v0.w); w.z = cvt_pk_bf16(v1.x, v1.y); w.w = cvt_pk_bf16(v1.z, v1.w); *(u32x4*)(dp16 + o2) = w; } } }
	v_lshlrev_b32_e32 v230, 16, v226
	v_and_b32_e32 v231, 0xffff0000, v226
	v_lshlrev_b32_e32 v232, 16, v227
	v_and_b32_e32 v233, 0xffff0000, v227
	v_lshlrev_b32_e32 v226, 16, v228
	v_and_b32_e32 v227, 0xffff0000, v228
	v_lshlrev_b32_e32 v228, 16, v229
	v_and_b32_e32 v229, 0xffff0000, v229
	v_pk_fma_f32 v[28:29], v[28:29], v[136:137], v[230:231]
	v_pk_fma_f32 v[30:31], v[30:31], v[138:139], v[232:233]
	v_pk_fma_f32 v[24:25], v[24:25], v[140:141], v[226:227]
	v_pk_fma_f32 v[26:27], v[26:27], v[142:143], v[228:229]
	v_cvt_pk_bf16_f32 v28, v28, v29
	v_cvt_pk_bf16_f32 v29, v30, v31
	v_cvt_pk_bf16_f32 v30, v24, v25
	v_cvt_pk_bf16_f32 v31, v26, v27
	s_waitcnt vmcnt(3)
	v_lshlrev_b32_e32 v230, 16, v144
	v_and_b32_e32 v231, 0xffff0000, v144
	v_lshlrev_b32_e32 v232, 16, v145
	v_and_b32_e32 v233, 0xffff0000, v145
	v_lshlrev_b32_e32 v144, 16, v146
	v_and_b32_e32 v145, 0xffff0000, v146
	v_lshlrev_b32_e32 v146, 16, v147
	v_and_b32_e32 v147, 0xffff0000, v147
	v_pk_fma_f32 v[36:37], v[36:37], v[128:129], v[230:231]
	v_pk_fma_f32 v[38:39], v[38:39], v[130:131], v[232:233]
	v_pk_fma_f32 v[32:33], v[32:33], v[132:133], v[144:145]
	v_pk_fma_f32 v[34:35], v[34:35], v[134:135], v[146:147]
	v_cvt_pk_bf16_f32 v36, v36, v37
	v_cvt_pk_bf16_f32 v37, v38, v39
	v_cvt_pk_bf16_f32 v38, v32, v33
	v_cvt_pk_bf16_f32 v39, v34, v35
	s_waitcnt vmcnt(2)
	v_lshlrev_b32_e32 v230, 16, v148
	v_and_b32_e32 v231, 0xffff0000, v148
	v_lshlrev_b32_e32 v232, 16, v149
	v_and_b32_e32 v233, 0xffff0000, v149
	v_lshlrev_b32_e32 v148, 16, v150
	v_and_b32_e32 v149, 0xffff0000, v150
	v_lshlrev_b32_e32 v150, 16, v151
	v_and_b32_e32 v151, 0xffff0000, v151
	v_pk_fma_f32 v[12:13], v[12:13], v[136:137], v[230:231]
	v_pk_fma_f32 v[14:15], v[14:15], v[138:139], v[232:233]
	v_pk_fma_f32 v[8:9], v[8:9], v[140:141], v[148:149]
	v_pk_fma_f32 v[10:11], v[10:11], v[142:143], v[150:151]
	v_cvt_pk_bf16_f32 v12, v12, v13
	v_cvt_pk_bf16_f32 v13, v14, v15
	v_cvt_pk_bf16_f32 v14, v8, v9
	v_cvt_pk_bf16_f32 v15, v10, v11
	s_waitcnt vmcnt(1)
	v_lshlrev_b32_e32 v230, 16, v152
	v_and_b32_e32 v231, 0xffff0000, v152
	v_lshlrev_b32_e32 v232, 16, v153
	v_and_b32_e32 v233, 0xffff0000, v153
	v_lshlrev_b32_e32 v152, 16, v154
	v_and_b32_e32 v153, 0xffff0000, v154
	v_lshlrev_b32_e32 v154, 16, v155
	v_and_b32_e32 v155, 0xffff0000, v155
	v_pk_fma_f32 v[20:21], v[20:21], v[128:129], v[230:231]
	v_pk_fma_f32 v[22:23], v[22:23], v[130:131], v[232:233]
	v_pk_fma_f32 v[16:17], v[16:17], v[132:133], v[152:153]
	v_pk_fma_f32 v[18:19], v[18:19], v[134:135], v[154:155]
	v_cvt_pk_bf16_f32 v20, v20, v21
	v_cvt_pk_bf16_f32 v21, v22, v23
	v_cvt_pk_bf16_f32 v22, v16, v17
	v_cvt_pk_bf16_f32 v23, v18, v19
	s_waitcnt vmcnt(0)
	v_lshlrev_b32_e32 v230, 16, v156
	v_and_b32_e32 v231, 0xffff0000, v156
	v_lshlrev_b32_e32 v232, 16, v157
	v_and_b32_e32 v233, 0xffff0000, v157
	v_lshlrev_b32_e32 v156, 16, v158
	v_and_b32_e32 v157, 0xffff0000, v158
	v_lshlrev_b32_e32 v158, 16, v159
	v_and_b32_e32 v159, 0xffff0000, v159
	v_pk_fma_f32 v[4:5], v[4:5], v[136:137], v[230:231]
	v_pk_fma_f32 v[6:7], v[6:7], v[138:139], v[232:233]
	v_pk_fma_f32 v[0:1], v[0:1], v[140:141], v[156:157]
	v_pk_fma_f32 v[2:3], v[2:3], v[142:143], v[158:159]
	v_cvt_pk_bf16_f32 v4, v4, v5
	v_cvt_pk_bf16_f32 v5, v6, v7
	v_cvt_pk_bf16_f32 v6, v0, v1
	v_cvt_pk_bf16_f32 v7, v2, v3
	v_lshl_add_u32 v234, v238, 1, v164
	global_store_dwordx4 v234, v[124:127], s[34:35]
	global_store_dwordx4 v234, v[108:111], s[34:35] offset:256
	v_lshl_add_u32 v235, v238, 1, v174
	global_store_dwordx4 v235, v[116:119], s[34:35]
	global_store_dwordx4 v235, v[100:103], s[34:35] offset:256
	v_lshl_add_u32 v234, v238, 1, v176
	global_store_dwordx4 v234, v[92:95], s[34:35]
	global_store_dwordx4 v234, v[84:87], s[34:35] offset:256
	v_lshl_add_u32 v235, v238, 1, v178
	global_store_dwordx4 v235, v[76:79], s[34:35]
	global_store_dwordx4 v235, v[68:71], s[34:35] offset:256
	v_lshl_add_u32 v234, v238, 1, v166
	global_store_dwordx4 v234, v[60:63], s[34:35]
	global_store_dwordx4 v234, v[52:55], s[34:35] offset:256
	v_lshl_add_u32 v235, v238, 1, v168
	global_store_dwordx4 v235, v[44:47], s[34:35]
	global_store_dwordx4 v235, v[28:31], s[34:35] offset:256
	v_lshl_add_u32 v234, v238, 1, v170
	global_store_dwordx4 v234, v[36:39], s[34:35]
	global_store_dwordx4 v234, v[12:15], s[34:35] offset:256
	v_lshl_add_u32 v235, v238, 1, v172
	global_store_dwordx4 v235, v[20:23], s[34:35]
	global_store_dwordx4 v235, v[4:7], s[34:35] offset:256
	s_andn2_b64 vcc, exec, s[6:7]
	s_mov_b64 s[6:7], -1
	s_cbranch_vccnz .LBB0_1113
	s_andn2_b64 vcc, exec, s[0:1]
	s_cbranch_vccnz .LBB0_1112
	s_barrier
	s_branch .LBB0_1112
